# GEMM site 8 residual epilogue: loads of step pairs issued together into spare fragment registers, counted vmcnt so loads no longer wait behind the previous step's stores
# baseline (speedup 1.0000x reference)
; DI float bflo(unsigned u) { return __uint_as_float(u << 16); }
;     DI void operator()(const f32x4 (&acc)[2][2][4][2], const Unit& u, int wr, int wc, int fr, int fq) const {
;     ...
;         const int col0 = u.pn * BM + wc * 32 + 4 * fq;
;         const float* mp = modl + (size_t)br * (NMOD * D) + (modidx & 15) * D + col0;
;         f32x4 cf[2][2];
; #pragma unroll
;         for (int bj = 0; bj < 2; ++bj)
; #pragma unroll
;             for (int n = 0; n < 2; ++n) cf[bj][n] = *(const f32x4*)(mp + bj * HALF + n * 16) * cs;
;         if (u.pm >= 128) {
;             float* hb = hc + (size_t)(u.pm - 128) * BM * D;
; #pragma unroll
;             for (int ai = 0; ai < 2; ++ai)
; #pragma unroll
;                 for (int m = 0; m < 4; ++m) { float* rowp = hb + (size_t)(ai * HALF + wr * 64 + m * 16 + fr) * D + col0;
; #pragma unroll
;                     for (int bj = 0; bj < 2; ++bj)
; #pragma unroll
;                         for (int n = 0; n < 2; ++n) { float* p = rowp + bj * HALF + n * 16; const f32x4 v = cf[bj][n] * acc[ai][bj][m][n];
;                             if (u.part) *(f32x4*)(part + (size_t)(u.part - 1) * MC * D + (p - hc)) = v; else *(f32x4*)p = *(const f32x4*)p + v; } }
;         } else {
;             const size_t tb = (size_t)u.pm * BM * D;
; #pragma unroll
;             for (int ai = 0; ai < 2; ++ai)
; #pragma unroll
;                 for (int mp2 = 0; mp2 < 2; ++mp2) { f32x4 hv[2][2][2];
; #pragma unroll
;                     for (int mm = 0; mm < 2; ++mm) { const size_t ro = tb + (size_t)(ai * HALF + wr * 64 + (2 * mp2 + mm) * 16 + fr) * D + col0;
; #pragma unroll
;                         for (int bj = 0; bj < 2; ++bj)
; #pragma unroll
;                             for (int n = 0; n < 2; ++n) { const size_t o = ro + bj * HALF + n * 16;
;                                 if (mode == 0) hv[mm][bj][n] = *(const f32x4*)(basel + o);
;                                 else { const u32x2 w = *(const u32x2*)((const bf16_t*)basel + o); hv[mm][bj][n] = (f32x4){bflo(w.x), bfhi(w.x), bflo(w.y), bfhi(w.y)}; } } }
;                     __builtin_amdgcn_sched_barrier(0);
; #pragma unroll
;                     for (int mm = 0; mm < 2; ++mm) { const size_t ro = tb + (size_t)(ai * HALF + wr * 64 + (2 * mp2 + mm) * 16 + fr) * D + col0;
; #pragma unroll
;                         for (int bj = 0; bj < 2; ++bj)
; #pragma unroll
.LBB0_1708:
	v_lshl_or_b32 v182, s30, 8, v193
	s_lshl_b64 s[30:31], s[34:35], 2
	s_add_u32 s30, s68, s30
	s_addc_u32 s31, s69, s31
	v_ashrrev_i32_e32 v183, 31, v182
	s_waitcnt vmcnt(0)
	v_lshl_add_u64 v[80:81], v[182:183], 2, s[30:31]
	s_mov_b64 s[30:31], 0x105000
	v_lshl_add_u64 v[82:83], v[80:81], 0, s[30:31]
	v_add_co_u32_e32 v80, vcc, 0x105000, v80
	s_cmpk_lt_i32 s8, 0x80
	s_nop 0
	v_addc_co_u32_e32 v81, vcc, 0, v81, vcc
	global_load_dwordx4 v[96:99], v[82:83], off offset:64
	global_load_dwordx4 v[88:91], v[82:83], off offset:512
	global_load_dwordx4 v[104:107], v[80:81], off
	s_nop 0
	global_load_dwordx4 v[80:83], v[82:83], off offset:576
	s_mov_b64 s[30:31], -1
	s_cbranch_scc0 .LBB0_1710
	s_ashr_i32 s9, s8, 31
	s_lshl_b64 s[30:31], s[8:9], 18
	v_lshl_add_u64 v[184:185], s[30:31], 0, v[182:183]
	v_lshl_add_u64 v[186:187], v[184:185], 0, v[146:147]
	v_lshl_add_u64 v[204:205], v[184:185], 0, v[148:149]
	v_lshl_add_u64 v[186:187], v[186:187], 1, s[12:13]
	v_lshl_add_u64 v[204:205], v[204:205], 1, s[12:13]
	global_load_dwordx2 v[196:197], v[186:187], off
	global_load_dwordx2 v[198:199], v[186:187], off offset:32
	global_load_dwordx2 v[200:201], v[186:187], off offset:256
	global_load_dwordx2 v[202:203], v[186:187], off offset:288
	global_load_dwordx2 v[206:207], v[204:205], off
	global_load_dwordx2 v[208:209], v[204:205], off offset:32
	global_load_dwordx2 v[210:211], v[204:205], off offset:256
	global_load_dwordx2 v[212:213], v[204:205], off offset:288
	v_lshl_add_u64 v[248:249], v[184:185], 0, v[150:151]
	v_lshl_add_u64 v[234:235], v[184:185], 0, v[152:153]
	v_lshl_add_u64 v[248:249], v[248:249], 1, s[12:13]
	v_lshl_add_u64 v[234:235], v[234:235], 1, s[12:13]
	global_load_dwordx2 v[242:243], v[248:249], off
	global_load_dwordx2 v[244:245], v[248:249], off offset:32
	global_load_dwordx2 v[246:247], v[248:249], off offset:256
	global_load_dwordx2 v[248:249], v[248:249], off offset:288
	global_load_dwordx2 v[250:251], v[234:235], off
	global_load_dwordx2 v[252:253], v[234:235], off offset:32
	global_load_dwordx2 v[232:233], v[234:235], off offset:256
	global_load_dwordx2 v[234:235], v[234:235], off offset:288
	s_waitcnt vmcnt(8)
	v_lshlrev_b32_e32 v214, 16, v196
	v_and_b32_e32 v215, 0xffff0000, v196
	v_lshlrev_b32_e32 v196, 16, v197
	v_and_b32_e32 v197, 0xffff0000, v197
	v_lshlrev_b32_e32 v216, 16, v198
	v_and_b32_e32 v217, 0xffff0000, v198
	v_lshlrev_b32_e32 v198, 16, v199
	v_and_b32_e32 v199, 0xffff0000, v199
	v_lshlrev_b32_e32 v218, 16, v200
	v_and_b32_e32 v219, 0xffff0000, v200
	v_lshlrev_b32_e32 v200, 16, v201
	v_and_b32_e32 v201, 0xffff0000, v201
	v_lshlrev_b32_e32 v220, 16, v202
	v_and_b32_e32 v221, 0xffff0000, v202
	v_lshlrev_b32_e32 v202, 16, v203
	v_and_b32_e32 v203, 0xffff0000, v203
	v_lshlrev_b32_e32 v222, 16, v206
	v_and_b32_e32 v223, 0xffff0000, v206
	v_lshlrev_b32_e32 v206, 16, v207
	v_and_b32_e32 v207, 0xffff0000, v207
	v_lshlrev_b32_e32 v224, 16, v208
	v_and_b32_e32 v225, 0xffff0000, v208
	v_lshlrev_b32_e32 v208, 16, v209
	v_and_b32_e32 v209, 0xffff0000, v209
	v_lshlrev_b32_e32 v226, 16, v210
	v_and_b32_e32 v227, 0xffff0000, v210
	v_lshlrev_b32_e32 v210, 16, v211
	v_and_b32_e32 v211, 0xffff0000, v211
	v_lshlrev_b32_e32 v228, 16, v212
	v_and_b32_e32 v229, 0xffff0000, v212
	v_lshlrev_b32_e32 v212, 16, v213
	v_and_b32_e32 v213, 0xffff0000, v213
	v_pk_fma_f32 v[196:197], v[142:143], v[106:107], v[196:197]
	v_pk_fma_f32 v[214:215], v[140:141], v[104:105], v[214:215]
	s_nop 0
	v_cvt_pk_bf16_f32 v214, v214, v215
	v_cvt_pk_bf16_f32 v215, v196, v197
	v_pk_fma_f32 v[196:197], v[138:139], v[98:99], v[198:199]
	v_pk_fma_f32 v[198:199], v[136:137], v[96:97], v[216:217]
	global_store_dwordx2 v[186:187], v[214:215], off
	v_cvt_pk_bf16_f32 v198, v198, v199
	v_cvt_pk_bf16_f32 v199, v196, v197
	global_store_dwordx2 v[186:187], v[198:199], off offset:32
	v_pk_fma_f32 v[196:197], v[134:135], v[90:91], v[200:201]
	v_pk_fma_f32 v[198:199], v[132:133], v[88:89], v[218:219]
	s_nop 0
	v_cvt_pk_bf16_f32 v198, v198, v199
	v_cvt_pk_bf16_f32 v199, v196, v197
	global_store_dwordx2 v[186:187], v[198:199], off offset:256
	v_pk_fma_f32 v[196:197], v[130:131], v[82:83], v[202:203]
	v_pk_fma_f32 v[198:199], v[128:129], v[80:81], v[220:221]
	s_nop 0
	v_cvt_pk_bf16_f32 v198, v198, v199
	v_cvt_pk_bf16_f32 v199, v196, v197
	global_store_dwordx2 v[186:187], v[198:199], off offset:288
	v_pk_fma_f32 v[186:187], v[126:127], v[106:107], v[206:207]
	v_pk_fma_f32 v[196:197], v[124:125], v[104:105], v[222:223]
	s_nop 0
	v_cvt_pk_bf16_f32 v196, v196, v197
	v_cvt_pk_bf16_f32 v197, v186, v187
	global_store_dwordx2 v[204:205], v[196:197], off
	v_pk_fma_f32 v[186:187], v[122:123], v[98:99], v[208:209]
	v_pk_fma_f32 v[196:197], v[120:121], v[96:97], v[224:225]
	s_nop 0
	v_cvt_pk_bf16_f32 v196, v196, v197
	v_cvt_pk_bf16_f32 v197, v186, v187
	global_store_dwordx2 v[204:205], v[196:197], off offset:32
	v_pk_fma_f32 v[186:187], v[118:119], v[90:91], v[210:211]
	v_pk_fma_f32 v[196:197], v[116:117], v[88:89], v[226:227]
	s_nop 0
	v_cvt_pk_bf16_f32 v196, v196, v197
	v_cvt_pk_bf16_f32 v197, v186, v187
	global_store_dwordx2 v[204:205], v[196:197], off offset:256
	v_pk_fma_f32 v[186:187], v[114:115], v[82:83], v[212:213]
	v_pk_fma_f32 v[196:197], v[112:113], v[80:81], v[228:229]
	s_nop 0
	v_cvt_pk_bf16_f32 v196, v196, v197
	v_cvt_pk_bf16_f32 v197, v186, v187
	global_store_dwordx2 v[204:205], v[196:197], off offset:288
	v_lshl_add_u64 v[186:187], v[184:185], 0, v[150:151]
	v_lshl_add_u64 v[204:205], v[184:185], 0, v[152:153]
	v_lshl_add_u64 v[186:187], v[186:187], 1, s[12:13]
	v_lshl_add_u64 v[204:205], v[204:205], 1, s[12:13]
	s_waitcnt vmcnt(8)
; DI unsigned cvtpk(float lo, float hi) { f32x2_t v = {lo, hi}; bf16x2_t b = __builtin_convertvector(v, bf16x2_t); return __builtin_bit_cast(unsigned, b); }
; DI float bflo(unsigned u) { return __uint_as_float(u << 16); }
; DI float bfhi(unsigned u) { return __uint_as_float(u & 0xffff0000u); }
;     DI void operator()(const f32x4 (&acc)[2][2][4][2], const Unit& u, int wr, int wc, int fr, int fq) const {
;     ...
;                 for (int mp2 = 0; mp2 < 2; ++mp2) { f32x4 hv[2][2][2];
; #pragma unroll
;                     for (int mm = 0; mm < 2; ++mm) { const size_t ro = tb + (size_t)(ai * HALF + wr * 64 + (2 * mp2 + mm) * 16 + fr) * D + col0;
; #pragma unroll
;                         for (int bj = 0; bj < 2; ++bj)
; #pragma unroll
;                             for (int n = 0; n < 2; ++n) { const size_t o = ro + bj * HALF + n * 16;
;                                 if (mode == 0) hv[mm][bj][n] = *(const f32x4*)(basel + o);
;                                 else { const u32x2 w = *(const u32x2*)((const bf16_t*)basel + o); hv[mm][bj][n] = (f32x4){bflo(w.x), bfhi(w.x), bflo(w.y), bfhi(w.y)}; } } }
;                     __builtin_amdgcn_sched_barrier(0);
; #pragma unroll
;                     for (int mm = 0; mm < 2; ++mm) { const size_t ro = tb + (size_t)(ai * HALF + wr * 64 + (2 * mp2 + mm) * 16 + fr) * D + col0;
; #pragma unroll
;                         for (int bj = 0; bj < 2; ++bj)
; #pragma unroll
;                             for (int n = 0; n < 2; ++n) { const size_t o = ro + bj * HALF + n * 16; const f32x4 v = hv[mm][bj][n] + cf[bj][n] * acc[ai][bj][2 * mp2 + mm][n];
;                                 if (mode == 2) *(f32x4*)(out + o) = v;
;                                 else { u32x2 w; w.x = cvtpk(v.x, v.y); w.y = cvtpk(v.z, v.w); *(u32x2*)((bf16_t*)out + o) = w; } } }
	v_lshlrev_b32_e32 v214, 16, v242
	v_and_b32_e32 v215, 0xffff0000, v242
	v_lshlrev_b32_e32 v196, 16, v243
	v_and_b32_e32 v197, 0xffff0000, v243
	v_lshlrev_b32_e32 v216, 16, v244
	v_and_b32_e32 v217, 0xffff0000, v244
	v_lshlrev_b32_e32 v198, 16, v245
	v_and_b32_e32 v199, 0xffff0000, v245
	v_lshlrev_b32_e32 v218, 16, v246
	v_and_b32_e32 v219, 0xffff0000, v246
	v_lshlrev_b32_e32 v200, 16, v247
	v_and_b32_e32 v201, 0xffff0000, v247
	v_lshlrev_b32_e32 v220, 16, v248
	v_and_b32_e32 v221, 0xffff0000, v248
	v_lshlrev_b32_e32 v202, 16, v249
	v_and_b32_e32 v203, 0xffff0000, v249
	v_lshlrev_b32_e32 v222, 16, v250
	v_and_b32_e32 v223, 0xffff0000, v250
	v_lshlrev_b32_e32 v206, 16, v251
	v_and_b32_e32 v207, 0xffff0000, v251
	v_lshlrev_b32_e32 v224, 16, v252
	v_and_b32_e32 v225, 0xffff0000, v252
	v_lshlrev_b32_e32 v208, 16, v253
	v_and_b32_e32 v209, 0xffff0000, v253
	v_lshlrev_b32_e32 v226, 16, v232
	v_and_b32_e32 v227, 0xffff0000, v232
	v_lshlrev_b32_e32 v210, 16, v233
	v_and_b32_e32 v211, 0xffff0000, v233
	v_lshlrev_b32_e32 v228, 16, v234
	v_and_b32_e32 v229, 0xffff0000, v234
	v_lshlrev_b32_e32 v212, 16, v235
	v_and_b32_e32 v213, 0xffff0000, v235
	v_pk_fma_f32 v[196:197], v[110:111], v[106:107], v[196:197]
	v_pk_fma_f32 v[214:215], v[108:109], v[104:105], v[214:215]
	s_nop 0
	v_cvt_pk_bf16_f32 v214, v214, v215
	v_cvt_pk_bf16_f32 v215, v196, v197
	v_pk_fma_f32 v[196:197], v[102:103], v[98:99], v[198:199]
	v_pk_fma_f32 v[198:199], v[100:101], v[96:97], v[216:217]
	global_store_dwordx2 v[186:187], v[214:215], off
	v_cvt_pk_bf16_f32 v198, v198, v199
	v_cvt_pk_bf16_f32 v199, v196, v197
	global_store_dwordx2 v[186:187], v[198:199], off offset:32
	v_pk_fma_f32 v[196:197], v[94:95], v[90:91], v[200:201]
	v_pk_fma_f32 v[198:199], v[92:93], v[88:89], v[218:219]
	s_nop 0
	v_cvt_pk_bf16_f32 v198, v198, v199
	v_cvt_pk_bf16_f32 v199, v196, v197
	global_store_dwordx2 v[186:187], v[198:199], off offset:256
	v_pk_fma_f32 v[196:197], v[86:87], v[82:83], v[202:203]
	v_pk_fma_f32 v[198:199], v[84:85], v[80:81], v[220:221]
	s_nop 0
	v_cvt_pk_bf16_f32 v198, v198, v199
	v_cvt_pk_bf16_f32 v199, v196, v197
	global_store_dwordx2 v[186:187], v[198:199], off offset:288
	v_pk_fma_f32 v[186:187], v[78:79], v[106:107], v[206:207]
	v_pk_fma_f32 v[196:197], v[76:77], v[104:105], v[222:223]
	s_nop 0
	v_cvt_pk_bf16_f32 v196, v196, v197
	v_cvt_pk_bf16_f32 v197, v186, v187
	global_store_dwordx2 v[204:205], v[196:197], off
	v_pk_fma_f32 v[186:187], v[74:75], v[98:99], v[208:209]
	v_pk_fma_f32 v[196:197], v[72:73], v[96:97], v[224:225]
	s_nop 0
	v_cvt_pk_bf16_f32 v196, v196, v197
	v_cvt_pk_bf16_f32 v197, v186, v187
	global_store_dwordx2 v[204:205], v[196:197], off offset:32
	v_pk_fma_f32 v[186:187], v[70:71], v[90:91], v[210:211]
	v_pk_fma_f32 v[196:197], v[68:69], v[88:89], v[226:227]
	s_nop 0
	v_cvt_pk_bf16_f32 v196, v196, v197
	v_cvt_pk_bf16_f32 v197, v186, v187
	global_store_dwordx2 v[204:205], v[196:197], off offset:256
	v_pk_fma_f32 v[186:187], v[66:67], v[82:83], v[212:213]
	v_pk_fma_f32 v[196:197], v[64:65], v[80:81], v[228:229]
	s_nop 0
	v_cvt_pk_bf16_f32 v196, v196, v197
	v_cvt_pk_bf16_f32 v197, v186, v187
	global_store_dwordx2 v[204:205], v[196:197], off offset:288
	v_lshl_add_u64 v[186:187], v[184:185], 0, v[154:155]
	v_lshl_add_u64 v[204:205], v[184:185], 0, v[156:157]
	v_lshl_add_u64 v[186:187], v[186:187], 1, s[12:13]
	v_lshl_add_u64 v[204:205], v[204:205], 1, s[12:13]
	global_load_dwordx2 v[196:197], v[186:187], off
	global_load_dwordx2 v[198:199], v[186:187], off offset:32
	global_load_dwordx2 v[200:201], v[186:187], off offset:256
	global_load_dwordx2 v[202:203], v[186:187], off offset:288
	global_load_dwordx2 v[206:207], v[204:205], off
	global_load_dwordx2 v[208:209], v[204:205], off offset:32
	global_load_dwordx2 v[210:211], v[204:205], off offset:256
	global_load_dwordx2 v[212:213], v[204:205], off offset:288
	v_lshl_add_u64 v[248:249], v[184:185], 0, v[158:159]
	v_lshl_add_u64 v[234:235], v[184:185], 0, v[160:161]
	v_lshl_add_u64 v[248:249], v[248:249], 1, s[12:13]
	v_lshl_add_u64 v[234:235], v[234:235], 1, s[12:13]
	global_load_dwordx2 v[242:243], v[248:249], off
	global_load_dwordx2 v[244:245], v[248:249], off offset:32
	global_load_dwordx2 v[246:247], v[248:249], off offset:256
	global_load_dwordx2 v[248:249], v[248:249], off offset:288
	global_load_dwordx2 v[250:251], v[234:235], off
	global_load_dwordx2 v[252:253], v[234:235], off offset:32
	global_load_dwordx2 v[232:233], v[234:235], off offset:256
	global_load_dwordx2 v[234:235], v[234:235], off offset:288
	s_waitcnt vmcnt(8)
; DI unsigned cvtpk(float lo, float hi) { f32x2_t v = {lo, hi}; bf16x2_t b = __builtin_convertvector(v, bf16x2_t); return __builtin_bit_cast(unsigned, b); }
; DI float bflo(unsigned u) { return __uint_as_float(u << 16); }
; DI float bfhi(unsigned u) { return __uint_as_float(u & 0xffff0000u); }
;     DI void operator()(const f32x4 (&acc)[2][2][4][2], const Unit& u, int wr, int wc, int fr, int fq) const {
;     ...
;                 for (int mp2 = 0; mp2 < 2; ++mp2) { f32x4 hv[2][2][2];
; #pragma unroll
;                     for (int mm = 0; mm < 2; ++mm) { const size_t ro = tb + (size_t)(ai * HALF + wr * 64 + (2 * mp2 + mm) * 16 + fr) * D + col0;
; #pragma unroll
;                         for (int bj = 0; bj < 2; ++bj)
; #pragma unroll
;                             for (int n = 0; n < 2; ++n) { const size_t o = ro + bj * HALF + n * 16;
;                                 if (mode == 0) hv[mm][bj][n] = *(const f32x4*)(basel + o);
;                                 else { const u32x2 w = *(const u32x2*)((const bf16_t*)basel + o); hv[mm][bj][n] = (f32x4){bflo(w.x), bfhi(w.x), bflo(w.y), bfhi(w.y)}; } } }
;                     __builtin_amdgcn_sched_barrier(0);
; #pragma unroll
;                     for (int mm = 0; mm < 2; ++mm) { const size_t ro = tb + (size_t)(ai * HALF + wr * 64 + (2 * mp2 + mm) * 16 + fr) * D + col0;
; #pragma unroll
;                         for (int bj = 0; bj < 2; ++bj)
; #pragma unroll
;                             for (int n = 0; n < 2; ++n) { const size_t o = ro + bj * HALF + n * 16; const f32x4 v = hv[mm][bj][n] + cf[bj][n] * acc[ai][bj][2 * mp2 + mm][n];
;                                 if (mode == 2) *(f32x4*)(out + o) = v;
;                                 else { u32x2 w; w.x = cvtpk(v.x, v.y); w.y = cvtpk(v.z, v.w); *(u32x2*)((bf16_t*)out + o) = w; } } }
	v_lshlrev_b32_e32 v214, 16, v196
	v_and_b32_e32 v215, 0xffff0000, v196
	v_lshlrev_b32_e32 v196, 16, v197
	v_and_b32_e32 v197, 0xffff0000, v197
	v_lshlrev_b32_e32 v216, 16, v198
	v_and_b32_e32 v217, 0xffff0000, v198
	v_lshlrev_b32_e32 v198, 16, v199
	v_and_b32_e32 v199, 0xffff0000, v199
	v_lshlrev_b32_e32 v218, 16, v200
	v_and_b32_e32 v219, 0xffff0000, v200
	v_lshlrev_b32_e32 v200, 16, v201
	v_and_b32_e32 v201, 0xffff0000, v201
	v_lshlrev_b32_e32 v220, 16, v202
	v_and_b32_e32 v221, 0xffff0000, v202
	v_lshlrev_b32_e32 v202, 16, v203
	v_and_b32_e32 v203, 0xffff0000, v203
	v_lshlrev_b32_e32 v222, 16, v206
	v_and_b32_e32 v223, 0xffff0000, v206
	v_lshlrev_b32_e32 v206, 16, v207
	v_and_b32_e32 v207, 0xffff0000, v207
	v_lshlrev_b32_e32 v224, 16, v208
	v_and_b32_e32 v225, 0xffff0000, v208
	v_lshlrev_b32_e32 v208, 16, v209
	v_and_b32_e32 v209, 0xffff0000, v209
	v_lshlrev_b32_e32 v226, 16, v210
	v_and_b32_e32 v227, 0xffff0000, v210
	v_lshlrev_b32_e32 v210, 16, v211
	v_and_b32_e32 v211, 0xffff0000, v211
	v_lshlrev_b32_e32 v228, 16, v212
	v_and_b32_e32 v229, 0xffff0000, v212
	v_lshlrev_b32_e32 v212, 16, v213
	v_and_b32_e32 v213, 0xffff0000, v213
	v_pk_fma_f32 v[196:197], v[62:63], v[106:107], v[196:197]
	v_pk_fma_f32 v[214:215], v[60:61], v[104:105], v[214:215]
	s_nop 0
	v_cvt_pk_bf16_f32 v214, v214, v215
	v_cvt_pk_bf16_f32 v215, v196, v197
	v_pk_fma_f32 v[196:197], v[58:59], v[98:99], v[198:199]
	v_pk_fma_f32 v[198:199], v[56:57], v[96:97], v[216:217]
	global_store_dwordx2 v[186:187], v[214:215], off
	v_cvt_pk_bf16_f32 v198, v198, v199
	v_cvt_pk_bf16_f32 v199, v196, v197
	global_store_dwordx2 v[186:187], v[198:199], off offset:32
	v_pk_fma_f32 v[196:197], v[54:55], v[90:91], v[200:201]
	v_pk_fma_f32 v[198:199], v[52:53], v[88:89], v[218:219]
	s_nop 0
	v_cvt_pk_bf16_f32 v198, v198, v199
	v_cvt_pk_bf16_f32 v199, v196, v197
	global_store_dwordx2 v[186:187], v[198:199], off offset:256
	v_pk_fma_f32 v[196:197], v[50:51], v[82:83], v[202:203]
	v_pk_fma_f32 v[198:199], v[48:49], v[80:81], v[220:221]
	s_nop 0
	v_cvt_pk_bf16_f32 v198, v198, v199
	v_cvt_pk_bf16_f32 v199, v196, v197
	global_store_dwordx2 v[186:187], v[198:199], off offset:288
	v_pk_fma_f32 v[186:187], v[46:47], v[106:107], v[206:207]
	v_pk_fma_f32 v[196:197], v[44:45], v[104:105], v[222:223]
	s_nop 0
	v_cvt_pk_bf16_f32 v196, v196, v197
	v_cvt_pk_bf16_f32 v197, v186, v187
	global_store_dwordx2 v[204:205], v[196:197], off
	v_pk_fma_f32 v[186:187], v[42:43], v[98:99], v[208:209]
	v_pk_fma_f32 v[196:197], v[40:41], v[96:97], v[224:225]
	s_nop 0
	v_cvt_pk_bf16_f32 v196, v196, v197
	v_cvt_pk_bf16_f32 v197, v186, v187
	global_store_dwordx2 v[204:205], v[196:197], off offset:32
	v_pk_fma_f32 v[186:187], v[38:39], v[90:91], v[210:211]
	v_pk_fma_f32 v[196:197], v[36:37], v[88:89], v[226:227]
	s_nop 0
	v_cvt_pk_bf16_f32 v196, v196, v197
	v_cvt_pk_bf16_f32 v197, v186, v187
	global_store_dwordx2 v[204:205], v[196:197], off offset:256
	v_pk_fma_f32 v[186:187], v[34:35], v[82:83], v[212:213]
	v_pk_fma_f32 v[196:197], v[32:33], v[80:81], v[228:229]
	s_nop 0
	v_cvt_pk_bf16_f32 v196, v196, v197
	v_cvt_pk_bf16_f32 v197, v186, v187
	global_store_dwordx2 v[204:205], v[196:197], off offset:288
	v_lshl_add_u64 v[186:187], v[184:185], 0, v[158:159]
	v_lshl_add_u64 v[184:185], v[184:185], 0, v[160:161]
	v_lshl_add_u64 v[186:187], v[186:187], 1, s[12:13]
	v_lshl_add_u64 v[184:185], v[184:185], 1, s[12:13]
	s_waitcnt vmcnt(8)
	v_lshlrev_b32_e32 v212, 16, v242
	v_and_b32_e32 v213, 0xffff0000, v242
	v_lshlrev_b32_e32 v196, 16, v243
	v_and_b32_e32 v197, 0xffff0000, v243
	v_lshlrev_b32_e32 v214, 16, v244
	v_and_b32_e32 v215, 0xffff0000, v244
	v_lshlrev_b32_e32 v198, 16, v245
	v_and_b32_e32 v199, 0xffff0000, v245
	v_lshlrev_b32_e32 v216, 16, v246
	v_and_b32_e32 v217, 0xffff0000, v246
	v_lshlrev_b32_e32 v200, 16, v247
	v_and_b32_e32 v201, 0xffff0000, v247
	v_lshlrev_b32_e32 v218, 16, v248
	v_and_b32_e32 v219, 0xffff0000, v248
	v_lshlrev_b32_e32 v202, 16, v249
	v_and_b32_e32 v203, 0xffff0000, v249
	v_lshlrev_b32_e32 v220, 16, v250
	v_and_b32_e32 v221, 0xffff0000, v250
	v_lshlrev_b32_e32 v204, 16, v251
	v_and_b32_e32 v205, 0xffff0000, v251
	v_lshlrev_b32_e32 v222, 16, v252
	v_and_b32_e32 v223, 0xffff0000, v252
	v_lshlrev_b32_e32 v206, 16, v253
	v_and_b32_e32 v207, 0xffff0000, v253
	v_lshlrev_b32_e32 v224, 16, v232
	v_and_b32_e32 v225, 0xffff0000, v232
	v_lshlrev_b32_e32 v208, 16, v233
	v_and_b32_e32 v209, 0xffff0000, v233
	v_lshlrev_b32_e32 v226, 16, v234
	v_and_b32_e32 v227, 0xffff0000, v234
	v_lshlrev_b32_e32 v210, 16, v235
	v_and_b32_e32 v211, 0xffff0000, v235
	v_pk_fma_f32 v[196:197], v[30:31], v[106:107], v[196:197]
	v_pk_fma_f32 v[212:213], v[28:29], v[104:105], v[212:213]
	s_nop 0
	v_cvt_pk_bf16_f32 v212, v212, v213
	v_cvt_pk_bf16_f32 v213, v196, v197
	v_pk_fma_f32 v[196:197], v[26:27], v[98:99], v[198:199]
	v_pk_fma_f32 v[198:199], v[24:25], v[96:97], v[214:215]
	global_store_dwordx2 v[186:187], v[212:213], off
	v_cvt_pk_bf16_f32 v198, v198, v199
	v_cvt_pk_bf16_f32 v199, v196, v197
	global_store_dwordx2 v[186:187], v[198:199], off offset:32
	v_pk_fma_f32 v[196:197], v[22:23], v[90:91], v[200:201]
	v_pk_fma_f32 v[198:199], v[20:21], v[88:89], v[216:217]
	s_nop 0
	v_cvt_pk_bf16_f32 v198, v198, v199
	v_cvt_pk_bf16_f32 v199, v196, v197
	global_store_dwordx2 v[186:187], v[198:199], off offset:256
	v_pk_fma_f32 v[196:197], v[18:19], v[82:83], v[202:203]
	v_pk_fma_f32 v[198:199], v[16:17], v[80:81], v[218:219]
	s_nop 0
	v_cvt_pk_bf16_f32 v198, v198, v199
	v_cvt_pk_bf16_f32 v199, v196, v197
	global_store_dwordx2 v[186:187], v[198:199], off offset:288
	v_pk_fma_f32 v[186:187], v[14:15], v[106:107], v[204:205]
	v_pk_fma_f32 v[196:197], v[12:13], v[104:105], v[220:221]
	s_nop 0
	v_cvt_pk_bf16_f32 v196, v196, v197
	v_cvt_pk_bf16_f32 v197, v186, v187
	global_store_dwordx2 v[184:185], v[196:197], off
	v_pk_fma_f32 v[186:187], v[10:11], v[98:99], v[206:207]
	v_pk_fma_f32 v[196:197], v[8:9], v[96:97], v[222:223]
	s_nop 0
	v_cvt_pk_bf16_f32 v196, v196, v197
	v_cvt_pk_bf16_f32 v197, v186, v187
	global_store_dwordx2 v[184:185], v[196:197], off offset:32
	v_pk_fma_f32 v[186:187], v[6:7], v[90:91], v[208:209]
	v_pk_fma_f32 v[196:197], v[4:5], v[88:89], v[224:225]
	s_nop 0
	v_cvt_pk_bf16_f32 v196, v196, v197
	v_cvt_pk_bf16_f32 v197, v186, v187
	global_store_dwordx2 v[184:185], v[196:197], off offset:256
	v_pk_fma_f32 v[186:187], v[2:3], v[82:83], v[210:211]
	v_pk_fma_f32 v[196:197], v[0:1], v[80:81], v[226:227]
	s_nop 0
	v_cvt_pk_bf16_f32 v196, v196, v197
	v_cvt_pk_bf16_f32 v197, v186, v187
	global_store_dwordx2 v[184:185], v[196:197], off offset:288
	s_mov_b64 s[30:31], 0
